# l0_prep conv loop: next item's four tap loads issued at the top of the current iteration (double buffer through copies)
# baseline (speedup 1.0000x reference)
; DI unsigned pk2(float lo, float hi) { f32x2 v = {lo, hi}; bf16x2_t b = __builtin_convertvector(v, bf16x2_t); return __builtin_bit_cast(unsigned, b); }
; DI float bflo(unsigned u) { return __uint_as_float(u << 16); }
; DI float bfhi(unsigned u) { return __uint_as_float(u & 0xffff0000u); }
; DI void phase_l0_prep(int wv, const ArgP a) {
;     ...
; #pragma unroll 2
;     for (int e = blockIdx.x * 512 + tid; e < S * 64; e += gridDim.x * 512) { const int t = e >> 6, c0 = (e & 63) * 8;
;         float acc[8];
; #pragma unroll
;         for (int j = 0; j < 8; ++j) acc[j] = cb[c0 + j];
; #pragma unroll
;         for (int k = 0; k < 4; ++k) { const int tt = t - 3 + k; if (tt < 0) continue;
;             const u32x4 v = *(const u32x4*)(Z + (size_t)tt * 1536 + c0);
;             const f32x4 w0 = *(const f32x4*)(cw + k * 512 + c0), w1 = *(const f32x4*)(cw + k * 512 + c0 + 4);
;             acc[0] += w0[0] * bflo(v.x); acc[1] += w0[1] * bfhi(v.x); acc[2] += w0[2] * bflo(v.y); acc[3] += w0[3] * bfhi(v.y);
;             acc[4] += w1[0] * bflo(v.z); acc[5] += w1[1] * bfhi(v.z); acc[6] += w1[2] * bflo(v.w); acc[7] += w1[3] * bfhi(v.w); }
;         u32x4 o; o.x = pk2(acc[0], acc[1]); o.y = pk2(acc[2], acc[3]); o.z = pk2(acc[4], acc[5]); o.w = pk2(acc[6], acc[7]);
;         *(u32x4*)(XC + (size_t)t * 512 + c0) = o; }
.LBB0_441:
	s_or_b64 exec, exec, s[0:1]
	s_mov_b64 s[12:13], s[82:83]
	s_waitcnt lgkmcnt(0)
	s_barrier
	s_load_dwordx2 s[0:1], s[12:13], 0xe8
	s_mov_b32 s4, s50
	v_mov_b32_e32 v18, v192
	s_waitcnt lgkmcnt(0)
	s_add_u32 s2, s0, 0x556b000
	v_lshl_add_u32 v19, s4, 6, v18
	v_add_u32_e32 v21, s33, v19
	s_mov_b32 s22, 0x100000
	s_addc_u32 s3, s1, 0
	v_cmp_gt_i32_e32 vcc, s22, v21
	s_and_saveexec_b64 s[8:9], vcc
	s_cbranch_execz .LBB0_462
	s_load_dword s14, s[88:89], 0x0
	s_load_dwordx4 s[4:7], s[12:13], 0x20
	s_add_u32 s10, s0, 0x856b000
	s_addc_u32 s11, s1, 0
	v_lshlrev_b32_e32 v20, 3, v21
	v_and_b32_e32 v10, 0x1f8, v20
	v_lshlrev_b32_e32 v8, 2, v10
	v_lshlrev_b32_e32 v10, 1, v10
	s_movk_i32 s25, 0xc00
	s_waitcnt lgkmcnt(0)
	s_add_u32 s12, s4, 0x1000
	s_addc_u32 s13, s5, 0
	s_lshl_b32 s23, s14, 9
	global_load_dwordx4 v[40:43], v8, s[4:5]
	global_load_dwordx4 v[44:47], v8, s[4:5] offset:16
	global_load_dwordx4 v[48:51], v8, s[4:5] offset:2048
	global_load_dwordx4 v[52:55], v8, s[4:5] offset:2064
	global_load_dwordx4 v[56:59], v8, s[12:13]
	global_load_dwordx4 v[60:63], v8, s[12:13] offset:16
	global_load_dwordx4 v[64:67], v8, s[12:13] offset:2048
	global_load_dwordx4 v[68:71], v8, s[12:13] offset:2064
	global_load_dwordx4 v[72:75], v8, s[6:7]
	global_load_dwordx4 v[76:79], v8, s[6:7] offset:16
	v_ashrrev_i32_e32 v129, 6, v21
	v_add_u32_e32 v130, -3, v129
	v_add_u32_e32 v131, -2, v129
	v_add_u32_e32 v132, -1, v129
	v_max_i32_e32 v130, 0, v130
	v_max_i32_e32 v131, 0, v131
	v_max_i32_e32 v132, 0, v132
	v_mad_u32_u24 v130, v130, s25, v10
	v_mad_u32_u24 v131, v131, s25, v10
	v_mad_u32_u24 v132, v132, s25, v10
	v_mad_u32_u24 v133, v129, s25, v10
	global_load_dwordx4 v[112:115], v130, s[2:3]
	global_load_dwordx4 v[116:119], v131, s[2:3]
	global_load_dwordx4 v[120:123], v132, s[2:3]
	global_load_dwordx4 v[124:127], v133, s[2:3]
	s_waitcnt vmcnt(0)
.Ll0c_loop:
	v_mov_b64_e32 v[80:81], v[112:113]
	v_mov_b64_e32 v[82:83], v[114:115]
	v_mov_b64_e32 v[84:85], v[116:117]
	v_mov_b64_e32 v[86:87], v[118:119]
	v_mov_b64_e32 v[88:89], v[120:121]
	v_mov_b64_e32 v[90:91], v[122:123]
	v_mov_b64_e32 v[92:93], v[124:125]
	v_mov_b64_e32 v[94:95], v[126:127]
	v_ashrrev_i32_e32 v16, 6, v21
	v_add_u32_e32 v128, s23, v21
	v_cmp_gt_i32_e32 vcc, s22, v128
	v_lshl_add_u32 v17, v16, 10, v10
	s_nop 0
	v_cndmask_b32_e32 v128, v21, v128, vcc
	v_ashrrev_i32_e32 v129, 6, v128
	v_add_u32_e32 v130, -3, v129
	v_add_u32_e32 v131, -2, v129
	v_add_u32_e32 v132, -1, v129
	v_max_i32_e32 v130, 0, v130
	v_max_i32_e32 v131, 0, v131
	v_max_i32_e32 v132, 0, v132
	v_mad_u32_u24 v130, v130, s25, v10
	v_mad_u32_u24 v131, v131, s25, v10
	v_mad_u32_u24 v132, v132, s25, v10
	v_mad_u32_u24 v133, v129, s25, v10
	global_load_dwordx4 v[112:115], v130, s[2:3]
	global_load_dwordx4 v[116:119], v131, s[2:3]
	global_load_dwordx4 v[120:123], v132, s[2:3]
	global_load_dwordx4 v[124:127], v133, s[2:3]
	v_cmp_gt_i32_e32 vcc, 3, v16
	v_mov_b32_e32 v24, v72
	v_mov_b32_e32 v25, v73
	v_mov_b32_e32 v26, v74
	v_mov_b32_e32 v27, v75
	v_mov_b32_e32 v28, v76
	v_mov_b32_e32 v29, v77
	v_mov_b32_e32 v30, v78
	v_mov_b32_e32 v31, v79
	s_cbranch_vccnz .Ll0c_edge
.Ll0c_taps:
	v_lshlrev_b32_e32 v100, 16, v80
	v_and_b32_e32 v101, 0xffff0000, v80
	v_lshlrev_b32_e32 v102, 16, v81
	v_and_b32_e32 v103, 0xffff0000, v81
	v_lshlrev_b32_e32 v104, 16, v82
	v_and_b32_e32 v105, 0xffff0000, v82
	v_lshlrev_b32_e32 v106, 16, v83
	v_and_b32_e32 v107, 0xffff0000, v83
	v_pk_fma_f32 v[24:25], v[40:41], v[100:101], v[24:25]
	v_pk_fma_f32 v[26:27], v[42:43], v[102:103], v[26:27]
	v_pk_fma_f32 v[28:29], v[44:45], v[104:105], v[28:29]
	v_pk_fma_f32 v[30:31], v[46:47], v[106:107], v[30:31]
	v_lshlrev_b32_e32 v100, 16, v84
	v_and_b32_e32 v101, 0xffff0000, v84
	v_lshlrev_b32_e32 v102, 16, v85
	v_and_b32_e32 v103, 0xffff0000, v85
	v_lshlrev_b32_e32 v104, 16, v86
	v_and_b32_e32 v105, 0xffff0000, v86
	v_lshlrev_b32_e32 v106, 16, v87
	v_and_b32_e32 v107, 0xffff0000, v87
	v_pk_fma_f32 v[24:25], v[48:49], v[100:101], v[24:25]
	v_pk_fma_f32 v[26:27], v[50:51], v[102:103], v[26:27]
	v_pk_fma_f32 v[28:29], v[52:53], v[104:105], v[28:29]
	v_pk_fma_f32 v[30:31], v[54:55], v[106:107], v[30:31]
	v_lshlrev_b32_e32 v100, 16, v88
	v_and_b32_e32 v101, 0xffff0000, v88
	v_lshlrev_b32_e32 v102, 16, v89
	v_and_b32_e32 v103, 0xffff0000, v89
	v_lshlrev_b32_e32 v104, 16, v90
	v_and_b32_e32 v105, 0xffff0000, v90
	v_lshlrev_b32_e32 v106, 16, v91
	v_and_b32_e32 v107, 0xffff0000, v91
	v_pk_fma_f32 v[24:25], v[56:57], v[100:101], v[24:25]
	v_pk_fma_f32 v[26:27], v[58:59], v[102:103], v[26:27]
	v_pk_fma_f32 v[28:29], v[60:61], v[104:105], v[28:29]
	v_pk_fma_f32 v[30:31], v[62:63], v[106:107], v[30:31]
	v_lshlrev_b32_e32 v100, 16, v92
	v_and_b32_e32 v101, 0xffff0000, v92
	v_lshlrev_b32_e32 v102, 16, v93
	v_and_b32_e32 v103, 0xffff0000, v93
	v_lshlrev_b32_e32 v104, 16, v94
	v_and_b32_e32 v105, 0xffff0000, v94
	v_lshlrev_b32_e32 v106, 16, v95
	v_and_b32_e32 v107, 0xffff0000, v95
	v_pk_fma_f32 v[24:25], v[64:65], v[100:101], v[24:25]
	v_pk_fma_f32 v[26:27], v[66:67], v[102:103], v[26:27]
	v_pk_fma_f32 v[28:29], v[68:69], v[104:105], v[28:29]
	v_pk_fma_f32 v[30:31], v[70:71], v[106:107], v[30:31]
	v_cvt_pk_bf16_f32 v108, v24, v25
	v_cvt_pk_bf16_f32 v109, v26, v27
	v_cvt_pk_bf16_f32 v110, v28, v29
	v_cvt_pk_bf16_f32 v111, v30, v31
	v_add_u32_e32 v21, s23, v21
	global_store_dwordx4 v17, v[108:111], s[10:11]
	s_waitcnt vmcnt(1)
	v_cmp_gt_i32_e32 vcc, s22, v21
	s_nop 1
	s_and_b64 exec, exec, vcc
	s_cbranch_execnz .Ll0c_loop
	s_branch .LBB0_462
